# attn pair tile: K frag reads issued up front, V frag reads hoisted above softmax, vmcnt(0) before PV removed
# speedup vs baseline: 1.0031x; 1.0029x over previous
; DI unsigned pack2(float lo, float hi) { f32x2_t v = {lo, hi}; bf16x2_t b = __builtin_convertvector(v, bf16x2_t); return __builtin_bit_cast(unsigned, b); }
; DI float xmax16(float v) { const unsigned x = __float_as_uint(v); auto r = __builtin_amdgcn_permlane16_swap(x, x, false, false); return fmaxf(__uint_as_float(r[0]), __uint_as_float(r[1])); }
; DI float xmax32(float v) { const unsigned x = __float_as_uint(v); auto r = __builtin_amdgcn_permlane32_swap(x, x, false, false); return fmaxf(__uint_as_float(r[0]), __uint_as_float(r[1])); }
; DI s16x4 tr16(const char* p) { return __builtin_bit_cast(s16x4, __builtin_amdgcn_ds_read_tr16_b64_v4i16((__attribute__((address_space(3))) s16x4*)p)); }
; DI void attn_softmax(f32x4 (&sc)[4], const float* tab, QG& G, int qpos, int dlt, int g, bf16x8 (&pf)[2]) {
;     ...
;     mx = xmax16(mx); mx = xmax32(mx);
;     const float mn = fmaxf(G.m, mx); const float alpha = __builtin_amdgcn_exp2f(G.m - mn); G.m = mn;
;     float ps = 0.f;
; #pragma unroll
;     for (int kt = 0; kt < 4; ++kt)
; #pragma unroll
;         for (int e = 0; e < 4; ++e) { const float pe = __builtin_amdgcn_exp2f(sc[kt][e] - mn); sc[kt][e] = pe; ps += pe; }
;     G.l = G.l * alpha + ps;
; #pragma unroll
;     for (int dt = 0; dt < 4; ++dt) G.o[dt] *= alpha;
; #pragma unroll
;     for (int ks = 0; ks < 2; ++ks) { uint4 w = {pack2(sc[2 * ks][0], sc[2 * ks][1]), pack2(sc[2 * ks][2], sc[2 * ks][3]), pack2(sc[2 * ks + 1][0], sc[2 * ks + 1][1]), pack2(sc[2 * ks + 1][2], sc[2 * ks + 1][3])};
;         pf[ks] = __builtin_bit_cast(bf16x8, w); }
; }
; DI void attn_tile2(const char* sk, const char* sv, const float* tab, QG& A, QG& B, int qposA, int dlt, int lane) {
;     ...
; #pragma unroll
;     for (int dt = 0; dt < 4; ++dt)
; #pragma unroll
;         for (int ks = 0; ks < 2; ++ks) {
;             const int vr = 32 * ks + 4 * g + (q >> 2); const int col = 16 * dt + 4 * (q & 3);
;             const s16x4 lo = tr16(sv + swz(vr, col >> 3) + (col & 7) * 2); const s16x4 hi = tr16(sv + swz(vr + 16, col >> 3) + (col & 7) * 2);
;             const bf16x8 vf = {lo[0], lo[1], lo[2], lo[3], hi[0], hi[1], hi[2], hi[3]};
;             A.o[dt] = __builtin_amdgcn_mfma_f32_16x16x32_bf16(vf, pa[ks], A.o[dt], 0, 0, 0);
;             B.o[dt] = __builtin_amdgcn_mfma_f32_16x16x32_bf16(vf, pb[ks], B.o[dt], 0, 0, 0);
;         }
.LBB0_398:
	v_max3_f32 v119, v118, v67, v119
	v_sub_f32_e32 v51, v100, v119
	v_exp_f32_e32 v54, v51
	v_sub_f32_e32 v52, v101, v119
	v_exp_f32_e32 v55, v52
	v_sub_f32_e32 v52, v96, v119
	v_exp_f32_e32 v56, v52
	v_sub_f32_e32 v52, v97, v119
	v_exp_f32_e32 v57, v52
	v_sub_f32_e32 v52, v90, v119
	v_add_f32_e32 v51, 0, v54
	v_exp_f32_e32 v58, v52
	v_sub_f32_e32 v52, v91, v119
	v_add_f32_e32 v51, v55, v51
	v_exp_f32_e32 v59, v52
	v_sub_f32_e32 v52, v88, v119
	v_add_f32_e32 v51, v56, v51
	v_exp_f32_e32 v60, v52
	v_sub_f32_e32 v52, v89, v119
	v_add_f32_e32 v51, v57, v51
	v_exp_f32_e32 v61, v52
	v_sub_f32_e32 v52, v102, v119
	v_add_f32_e32 v51, v58, v51
	v_exp_f32_e32 v62, v52
	v_sub_f32_e32 v52, v103, v119
	v_add_f32_e32 v51, v59, v51
	v_exp_f32_e32 v63, v52
	v_sub_f32_e32 v52, v98, v119
	v_add_f32_e32 v51, v60, v51
	v_exp_f32_e32 v64, v52
	v_sub_f32_e32 v52, v99, v119
	v_add_f32_e32 v51, v61, v51
	v_exp_f32_e32 v65, v52
	v_sub_f32_e32 v52, v94, v119
	v_add_f32_e32 v51, v62, v51
	v_exp_f32_e32 v88, v52
	v_sub_f32_e32 v52, v95, v119
	v_add_f32_e32 v51, v63, v51
	v_exp_f32_e32 v89, v52
	v_sub_f32_e32 v52, v92, v119
	v_cvt_pk_bf16_f32 v54, v54, v55
	v_cvt_pk_bf16_f32 v55, v56, v57
	v_cvt_pk_bf16_f32 v56, v58, v59
	v_mov_b32_e32 v58, v66
	v_sub_f32_e32 v50, v118, v119
	v_add_f32_e32 v51, v64, v51
	v_exp_f32_e32 v90, v52
	v_permlane16_swap_b32_e32 v66, v58
	v_add_f32_e32 v51, v65, v51
	v_sub_f32_e32 v52, v93, v119
	v_exp_f32_e32 v50, v50
	v_max_f32_e32 v58, v58, v58
	v_max_f32_e32 v59, v66, v66
	v_add_f32_e32 v51, v88, v51
	v_exp_f32_e32 v91, v52
	v_max_f32_e32 v58, v59, v58
	v_add_f32_e32 v51, v89, v51
	v_mov_b32_e32 v59, v58
	v_add_f32_e32 v51, v90, v51
	s_nop 0
	v_permlane32_swap_b32_e32 v58, v59
	v_pk_mul_f32 v[52:53], v[48:49], v[50:51] op_sel_hi:[1,0]
	v_cvt_pk_bf16_f32 v48, v88, v89
	v_max3_f32 v88, v117, v58, v59
	v_add_f32_e32 v67, v91, v51
	v_sub_f32_e32 v59, v74, v88
	v_fmac_f32_e32 v67, v87, v50
	v_pk_mul_f32 v[36:37], v[36:37], v[50:51] op_sel_hi:[1,0]
	v_pk_mul_f32 v[34:35], v[34:35], v[50:51] op_sel_hi:[1,0]
	v_pk_mul_f32 v[44:45], v[44:45], v[50:51] op_sel_hi:[1,0]
	v_pk_mul_f32 v[42:43], v[42:43], v[50:51] op_sel_hi:[1,0]
	v_pk_mul_f32 v[40:41], v[40:41], v[50:51] op_sel_hi:[1,0]
	v_pk_mul_f32 v[38:39], v[38:39], v[50:51] op_sel_hi:[1,0]
	v_pk_mul_f32 v[50:51], v[46:47], v[50:51] op_sel_hi:[1,0]
	v_cvt_pk_bf16_f32 v46, v62, v63
	v_cvt_pk_bf16_f32 v57, v60, v61
	v_exp_f32_e32 v62, v59
	v_sub_f32_e32 v60, v75, v88
	v_exp_f32_e32 v63, v60
	v_sub_f32_e32 v60, v72, v88
	v_cvt_pk_bf16_f32 v47, v64, v65
	v_exp_f32_e32 v64, v60
	v_sub_f32_e32 v60, v73, v88
	v_exp_f32_e32 v65, v60
	v_sub_f32_e32 v60, v70, v88
	v_add_f32_e32 v59, 0, v62
	v_exp_f32_e32 v70, v60
	v_sub_f32_e32 v60, v71, v88
	v_add_f32_e32 v59, v63, v59
	v_exp_f32_e32 v71, v60
	v_sub_f32_e32 v60, v68, v88
	v_add_f32_e32 v59, v64, v59
	v_exp_f32_e32 v68, v60
	v_sub_f32_e32 v60, v69, v88
	v_add_f32_e32 v59, v65, v59
	v_exp_f32_e32 v69, v60
	v_sub_f32_e32 v60, v104, v88
	v_add_f32_e32 v59, v70, v59
	v_exp_f32_e32 v72, v60
	v_sub_f32_e32 v60, v105, v88
	v_add_f32_e32 v59, v71, v59
	v_exp_f32_e32 v73, v60
	v_sub_f32_e32 v60, v80, v88
	v_add_f32_e32 v59, v68, v59
	v_exp_f32_e32 v74, v60
	v_sub_f32_e32 v60, v81, v88
	v_add_f32_e32 v59, v69, v59
	v_exp_f32_e32 v75, v60
	v_sub_f32_e32 v60, v78, v88
	v_add_f32_e32 v59, v72, v59
	v_exp_f32_e32 v78, v60
	v_sub_f32_e32 v60, v79, v88
	v_add_f32_e32 v59, v73, v59
	v_exp_f32_e32 v79, v60
	v_sub_f32_e32 v60, v76, v88
	v_add_f32_e32 v59, v74, v59
	v_exp_f32_e32 v76, v60
	v_sub_f32_e32 v60, v77, v88
	v_sub_f32_e32 v58, v117, v88
	v_add_f32_e32 v59, v75, v59
	v_exp_f32_e32 v77, v60
	v_add_f32_e32 v59, v78, v59
	v_exp_f32_e32 v58, v58
	v_add_f32_e32 v59, v79, v59
	v_add_f32_e32 v59, v76, v59
	v_add_f32_e32 v66, v77, v59
	v_fmac_f32_e32 v66, v86, v58
	v_pk_mul_f32 v[4:5], v[4:5], v[58:59] op_sel_hi:[1,0]
	v_pk_mul_f32 v[2:3], v[2:3], v[58:59] op_sel_hi:[1,0]
	v_pk_mul_f32 v[8:9], v[8:9], v[58:59] op_sel_hi:[1,0]
	v_pk_mul_f32 v[6:7], v[6:7], v[58:59] op_sel_hi:[1,0]
	v_pk_mul_f32 v[12:13], v[12:13], v[58:59] op_sel_hi:[1,0]
	v_pk_mul_f32 v[10:11], v[10:11], v[58:59] op_sel_hi:[1,0]
	v_pk_mul_f32 v[60:61], v[16:17], v[58:59] op_sel_hi:[1,0]
	v_pk_mul_f32 v[58:59], v[14:15], v[58:59] op_sel_hi:[1,0]
	v_cvt_pk_bf16_f32 v14, v72, v73
	v_cvt_pk_bf16_f32 v62, v62, v63
	v_cvt_pk_bf16_f32 v63, v64, v65
	v_cvt_pk_bf16_f32 v64, v70, v71
	v_cvt_pk_bf16_f32 v65, v68, v69
	s_waitcnt lgkmcnt(0)
	v_mfma_f32_16x16x32_bf16 v[34:37], v[124:127], v[54:57], v[34:37]
	v_cvt_pk_bf16_f32 v49, v90, v91
	v_cvt_pk_bf16_f32 v15, v74, v75
	v_cvt_pk_bf16_f32 v16, v78, v79
	v_mfma_f32_16x16x32_bf16 v[2:5], v[124:127], v[62:65], v[2:5]
	v_cvt_pk_bf16_f32 v17, v76, v77
	v_mov_b32_e32 v87, v67
	v_mfma_f32_16x16x32_bf16 v[34:37], v[128:131], v[46:49], v[34:37]
	v_mov_b32_e32 v86, v66
	v_mov_b32_e32 v118, v119
	v_mov_b32_e32 v117, v88
	v_mfma_f32_16x16x32_bf16 v[2:5], v[128:131], v[14:17], v[2:5]
	v_mfma_f32_16x16x32_bf16 v[42:45], v[132:135], v[54:57], v[42:45]
	v_mfma_f32_16x16x32_bf16 v[6:9], v[132:135], v[62:65], v[6:9]
	v_mfma_f32_16x16x32_bf16 v[42:45], v[136:139], v[46:49], v[42:45]
	v_mfma_f32_16x16x32_bf16 v[6:9], v[136:139], v[14:17], v[6:9]
	v_mfma_f32_16x16x32_bf16 v[38:41], v[140:143], v[54:57], v[38:41]
	v_mfma_f32_16x16x32_bf16 v[10:13], v[140:143], v[62:65], v[10:13]
	v_mfma_f32_16x16x32_bf16 v[38:41], v[144:147], v[46:49], v[38:41]
	v_mfma_f32_16x16x32_bf16 v[10:13], v[144:147], v[14:17], v[10:13]
	v_mfma_f32_16x16x32_bf16 v[50:53], v[148:151], v[54:57], v[50:53]
	v_mfma_f32_16x16x32_bf16 v[54:57], v[148:151], v[62:65], v[58:61]
	v_mfma_f32_16x16x32_bf16 v[46:49], v[152:155], v[46:49], v[50:53]
	v_mfma_f32_16x16x32_bf16 v[14:17], v[152:155], v[14:17], v[54:57]

; DI s16x4 tr16(const char* p) { return __builtin_bit_cast(s16x4, __builtin_amdgcn_ds_read_tr16_b64_v4i16((__attribute__((address_space(3))) s16x4*)p)); }
; DI void attn_softmax(f32x4 (&sc)[4], const float* tab, QG& G, int qpos, int dlt, int g, bf16x8 (&pf)[2]) {
;     ...
;     } else {
; #pragma unroll
;         for (int kt = 0; kt < 4; ++kt)
; #pragma unroll
;             for (int e = 0; e < 4; ++e) { const int key = 16 * kt + 4 * g + e; int rel = qpos - key + dlt * 64; rel = rel < -128 ? -128 : (rel > 128 ? 128 : rel);
;                 const float s = sc[kt][e] * C2 + tab[rel + 128]; sc[kt][e] = s; mx = fmaxf(mx, s); }
; DI void attn_tile2(const char* sk, const char* sv, const float* tab, QG& A, QG& B, int qposA, int dlt, int lane) {
;     ...
;     for (int kt = 0; kt < 4; ++kt) {
;         const bf16x8 a0 = *(const bf16x8*)(sk + swz(16 * kt + q, g)); const bf16x8 a1 = *(const bf16x8*)(sk + swz(16 * kt + q, 4 + g));
;         f32x4 x = {0.f, 0.f, 0.f, 0.f}, y = {0.f, 0.f, 0.f, 0.f};
;         x = __builtin_amdgcn_mfma_f32_16x16x32_bf16(a0, A.q0, x, 0, 0, 0); y = __builtin_amdgcn_mfma_f32_16x16x32_bf16(a0, B.q0, y, 0, 0, 0);
;         x = __builtin_amdgcn_mfma_f32_16x16x32_bf16(a1, A.q1, x, 0, 0, 0); y = __builtin_amdgcn_mfma_f32_16x16x32_bf16(a1, B.q1, y, 0, 0, 0);
;         sa[kt] = x; sb[kt] = y;
;     }
;     ...
;             const int vr = 32 * ks + 4 * g + (q >> 2); const int col = 16 * dt + 4 * (q & 3);
;             const s16x4 lo = tr16(sv + swz(vr, col >> 3) + (col & 7) * 2); const s16x4 hi = tr16(sv + swz(vr + 16, col >> 3) + (col & 7) * 2);
.LBB0_406:
	s_cmp_gt_u32 s93, 8
	s_cbranch_scc1 .LBB0_415
	s_lshl_b32 s2, s92, 13
	v_add_u32_e32 v54, s2, v115
	v_add_u32_e32 v78, v54, v107
	v_add_u32_e32 v79, v54, v108
	ds_read_b128 v[124:127], v78
	ds_read_b128 v[128:131], v79
	ds_read_b128 v[132:135], v78 offset:2048
	ds_read_b128 v[136:139], v79 offset:2048
	ds_read_b128 v[140:143], v78 offset:4096
	ds_read_b128 v[144:147], v79 offset:4096
	ds_read_b128 v[148:151], v78 offset:6144
	ds_read_b128 v[152:155], v79 offset:6144
	s_cmp_lt_u32 s93, 3
	v_add_u32_e32 v92, -16, v116
	s_mov_b64 s[30:31], -1
	s_cselect_b64 s[28:29], -1, 0
	s_cmp_gt_u32 s93, 2
	v_min_i32_e32 v104, 0x80, v92
	v_add_u32_e32 v156, s2, v109
	v_add3_u32 v157, v156, v111, v110
	v_add3_u32 v204, v156, v112, v110
	v_add3_u32 v205, v156, v113, v110
	v_add3_u32 v206, v156, v114, v110
	s_waitcnt lgkmcnt(6)
	v_mfma_f32_16x16x32_bf16 v[58:61], v[124:127], v[18:21], 0
	v_mfma_f32_16x16x32_bf16 v[50:53], v[124:127], v[26:29], 0
	v_mfma_f32_16x16x32_bf16 v[66:69], v[128:131], v[22:25], v[58:61]
	v_mfma_f32_16x16x32_bf16 v[50:53], v[128:131], v[30:33], v[50:53]
	s_waitcnt lgkmcnt(4)
	v_mfma_f32_16x16x32_bf16 v[62:65], v[132:135], v[18:21], 0
	v_mfma_f32_16x16x32_bf16 v[54:57], v[132:135], v[26:29], 0
	v_mfma_f32_16x16x32_bf16 v[74:77], v[136:139], v[22:25], v[62:65]
	v_mfma_f32_16x16x32_bf16 v[58:61], v[136:139], v[30:33], v[54:57]
	s_waitcnt lgkmcnt(2)
	v_mfma_f32_16x16x32_bf16 v[70:73], v[140:143], v[18:21], 0
	v_mfma_f32_16x16x32_bf16 v[54:57], v[140:143], v[26:29], 0
	v_mfma_f32_16x16x32_bf16 v[70:73], v[144:147], v[22:25], v[70:73]
	v_mfma_f32_16x16x32_bf16 v[54:57], v[144:147], v[30:33], v[54:57]
	s_waitcnt lgkmcnt(0)
	v_mfma_f32_16x16x32_bf16 v[78:81], v[148:151], v[18:21], 0
	v_mfma_f32_16x16x32_bf16 v[62:65], v[148:151], v[26:29], 0
	v_mfma_f32_16x16x32_bf16 v[78:81], v[152:155], v[22:25], v[78:81]
	v_mfma_f32_16x16x32_bf16 v[62:65], v[152:155], v[30:33], v[62:65]
	ds_read_b64_tr_b16 v[124:125], v157 offset:24576
	ds_read_b64_tr_b16 v[126:127], v157 offset:26624
	ds_read_b64_tr_b16 v[128:129], v157 offset:28672
	ds_read_b64_tr_b16 v[130:131], v157 offset:30720
	ds_read_b64_tr_b16 v[132:133], v204 offset:24576
	ds_read_b64_tr_b16 v[134:135], v204 offset:26624
	ds_read_b64_tr_b16 v[136:137], v204 offset:28672
	ds_read_b64_tr_b16 v[138:139], v204 offset:30720
	ds_read_b64_tr_b16 v[140:141], v205 offset:24576
	ds_read_b64_tr_b16 v[142:143], v205 offset:26624
	ds_read_b64_tr_b16 v[144:145], v205 offset:28672
	ds_read_b64_tr_b16 v[146:147], v205 offset:30720
	ds_read_b64_tr_b16 v[148:149], v206 offset:24576
	ds_read_b64_tr_b16 v[150:151], v206 offset:26624
	ds_read_b64_tr_b16 v[152:153], v206 offset:28672
	ds_read_b64_tr_b16 v[154:155], v206 offset:30720
	s_cbranch_scc1 .LBB0_409
	v_subrev_u32_e32 v89, 17, v116
	v_min_i32_e32 v94, 0x91, v92
	v_min_i32_e32 v89, 0x80, v89
	v_min_i32_e32 v90, 0x82, v92
	v_min_i32_e32 v91, 0x83, v92
	v_lshl_add_u32 v95, v94, 2, 0
	v_min_i32_e32 v94, 0x92, v92
	v_lshl_add_u32 v88, v104, 2, 0
	v_lshl_add_u32 v89, v89, 2, 0
	v_lshl_add_u32 v90, v90, 2, 0
	v_lshl_add_u32 v91, v91, 2, 0
	v_min_i32_e32 v93, 0x90, v92
	v_lshl_add_u32 v96, v94, 2, 0
	v_min_i32_e32 v94, 0x93, v92
	v_lshl_add_u32 v93, v93, 2, 0
	v_lshl_add_u32 v97, v94, 2, 0
	ds_read_b32 v88, v88 offset:49664
	ds_read_b32 v89, v89 offset:49664
	ds_read_b32 v90, v90 offset:49656
	ds_read_b32 v91, v91 offset:49652
	ds_read_b32 v94, v93 offset:49600
	ds_read_b32 v95, v95 offset:49596
	ds_read_b32 v98, v96 offset:49592
	ds_read_b32 v99, v97 offset:49588
	s_waitcnt lgkmcnt(0)
	v_pk_fma_f32 v[100:101], v[66:67], s[10:11], v[88:89] op_sel_hi:[1,0,1]
	v_pk_fma_f32 v[96:97], v[68:69], s[10:11], v[90:91] op_sel_hi:[1,0,1]
	v_max3_f32 v88, v100, s65, v101
	v_max3_f32 v88, v88, v96, v97
	v_pk_fma_f32 v[90:91], v[74:75], s[10:11], v[94:95] op_sel_hi:[1,0,1]
	v_min_i32_e32 v94, 0xa1, v92
	v_max3_f32 v93, v88, v90, v91
	v_pk_fma_f32 v[88:89], v[76:77], s[10:11], v[98:99] op_sel_hi:[1,0,1]
	v_min_i32_e32 v95, 0xa2, v92
	v_max3_f32 v98, v93, v88, v89
	v_min_i32_e32 v93, 0xa0, v92
	v_lshl_add_u32 v93, v93, 2, 0
	v_lshl_add_u32 v94, v94, 2, 0
	v_lshl_add_u32 v95, v95, 2, 0
	v_min_i32_e32 v99, 0xa3, v92
	v_min_i32_e32 v102, 0xb0, v92
	v_min_i32_e32 v103, 0xb1, v92
	v_min_i32_e32 v105, 0xb2, v92
	v_min_i32_e32 v92, 0xb3, v92
	v_lshl_add_u32 v99, v99, 2, 0
	v_lshl_add_u32 v102, v102, 2, 0
	v_lshl_add_u32 v103, v103, 2, 0
	v_lshl_add_u32 v105, v105, 2, 0
	v_lshl_add_u32 v119, v92, 2, 0
	ds_read_b32 v92, v93 offset:49536
	ds_read_b32 v93, v94 offset:49532
	ds_read_b32 v94, v95 offset:49528
	ds_read_b32 v95, v99 offset:49524
	ds_read_b32 v120, v102 offset:49472
	ds_read_b32 v121, v103 offset:49468
	ds_read_b32 v122, v105 offset:49464
	ds_read_b32 v123, v119 offset:49460
	s_waitcnt lgkmcnt(0)
	v_pk_fma_f32 v[102:103], v[70:71], s[10:11], v[92:93] op_sel_hi:[1,0,1]
	s_mov_b64 s[30:31], 0
	v_max3_f32 v92, v98, v102, v103
	v_pk_fma_f32 v[98:99], v[72:73], s[10:11], v[94:95] op_sel_hi:[1,0,1]
	v_pk_fma_f32 v[94:95], v[78:79], s[10:11], v[120:121] op_sel_hi:[1,0,1]
	v_max3_f32 v92, v92, v98, v99
	v_max3_f32 v105, v92, v94, v95
	v_pk_fma_f32 v[92:93], v[80:81], s[10:11], v[122:123] op_sel_hi:[1,0,1]
	s_nop 0
	v_max3_f32 v105, v105, v92, v93
